# attention: next-tile K/V LDS writes issued right after the second-half QK MFMAs (their completion overlaps softmax and PV instead of stalling before the tile barrier)
# baseline (speedup 1.0000x reference)
; #define LAS __attribute__((address_space(3)))
; #define MFMA32(a, b, c) __builtin_amdgcn_mfma_f32_32x32x16_bf16(a, b, c, 0, 0, 0)
; #define ATT_WRITE(bufp) do { *(LAS u32x4*)((bufp) + kofs0) = kr0; if (tid < 256) *(LAS u32x4*)((bufp) + kofs1) = kr1; *(LAS u32x4*)((bufp) + vofs) = vr; } while (0)
; __device__ __forceinline__ void attn_unit(int bh, int qb, const bf16_t* QKV, const bf16_t* KF, const float* cstab, const float* qg, bf16_t* MIX, LAS unsigned char* lds) {
;     ...
;             for (int d0 = 0; d0 < 6; ++d0) p = MFMA32(kfr[d0], qf[d0], p);
;             __builtin_amdgcn_s_setprio(0);
;             if (key0 + 31 > qw) {
; #pragma unroll
;                 for (int r = 0; r < 16; ++r) { const int key = key0 + (r & 3) + 8 * (r >> 2) + 4 * hi; if (key > q) p[r] = -1e30f; }
;     ...
;         if (t + 1 < NT) { LAS unsigned char* nb = lds + ((t + 1) & 1) * BUFB; ATT_WRITE(nb); }
.LBB0_1069:
	s_setprio 1
	s_waitcnt lgkmcnt(5)
	v_mfma_f32_32x32x16_bf16 v[48:63], v[202:205], v[74:77], v[32:47]
	s_waitcnt lgkmcnt(4)
	v_mfma_f32_32x32x16_bf16 v[48:63], v[206:209], v[78:81], v[48:63]
	s_waitcnt lgkmcnt(3)
	v_mfma_f32_32x32x16_bf16 v[48:63], v[210:213], v[82:85], v[48:63]
	s_waitcnt lgkmcnt(2)
	v_mfma_f32_32x32x16_bf16 v[48:63], v[214:217], v[90:93], v[48:63]
	s_waitcnt lgkmcnt(1)
	v_mfma_f32_32x32x16_bf16 v[48:63], v[218:221], v[94:97], v[48:63]
	s_waitcnt lgkmcnt(0)
	v_mfma_f32_32x32x16_bf16 v[48:63], v[222:225], v[98:101], v[48:63]
	s_andn2_b64 vcc, exec, s[4:5]
	s_cbranch_vccnz .Lwskip_a
	s_cmp_eq_u32 s23, 1
	s_cselect_b32 s100, 0x6400, 0
	s_add_i32 s23, s100, 0
	v_add_u32_e32 v173, s23, v103
	s_waitcnt vmcnt(1)
	ds_write_b128 v173, v[70:73]
	s_and_saveexec_b64 s[100:101], s[6:7]
	v_add_u32_e32 v173, s23, v135
	ds_write_b128 v173, v[66:69]
	s_or_b64 exec, exec, s[100:101]
	v_add_u32_e32 v173, s23, v104
	s_waitcnt vmcnt(0)
	ds_write_b128 v173, v[86:89] offset:13312
.Lwskip_a:
	v_add_u32_e32 v172, v119, v115
	ds_read_b64_tr_b16 v[156:157], v172 offset:19456
	ds_read_b64_tr_b16 v[158:159], v172 offset:20992
	ds_read_b64_tr_b16 v[160:161], v172 offset:22528
	ds_read_b64_tr_b16 v[162:163], v172 offset:24064
	ds_read_b64_tr_b16 v[164:165], v172 offset:19520
	ds_read_b64_tr_b16 v[166:167], v172 offset:21056
	ds_read_b64_tr_b16 v[168:169], v172 offset:22592
	ds_read_b64_tr_b16 v[170:171], v172 offset:24128
	s_setprio 0
	s_add_i32 s44, s43, 0x7f
	s_cmp_le_i32 s44, s37
	s_cbranch_scc1 .LBB0_1071
	v_add_u32_e32 v120, s43, v105
	v_add_u32_e32 v121, 0x60, v120
	v_cmp_lt_i32_e32 vcc, v121, v139
	s_nop 4
	v_cndmask_b32_e32 v49, v239, v49, vcc
	v_cmp_le_i32_e32 vcc, v121, v139
	v_add_u32_e32 v121, 0x62, v120
	s_nop 0
	v_cndmask_b32_e32 v48, v239, v48, vcc
	v_cmp_le_i32_e32 vcc, v121, v139
	v_add_u32_e32 v121, 0x63, v120
	s_nop 0
	v_cndmask_b32_e32 v50, v239, v50, vcc
	v_cmp_le_i32_e32 vcc, v121, v139
	v_add_u32_e32 v121, 0x68, v120
	s_nop 0
	v_cndmask_b32_e32 v51, v239, v51, vcc
	v_cmp_le_i32_e32 vcc, v121, v139
	v_add_u32_e32 v121, 0x69, v120
	s_nop 0
	v_cndmask_b32_e32 v52, v239, v52, vcc
	v_cmp_le_i32_e32 vcc, v121, v139
	v_add_u32_e32 v121, 0x6a, v120
	s_nop 0
	v_cndmask_b32_e32 v53, v239, v53, vcc
	v_cmp_le_i32_e32 vcc, v121, v139
	v_add_u32_e32 v121, 0x6b, v120
	s_nop 0
	v_cndmask_b32_e32 v54, v239, v54, vcc
	v_cmp_le_i32_e32 vcc, v121, v139
	v_add_u32_e32 v121, 0x70, v120
	s_nop 0
	v_cndmask_b32_e32 v55, v239, v55, vcc
	v_cmp_le_i32_e32 vcc, v121, v139
	v_add_u32_e32 v121, 0x71, v120
	s_nop 0
	v_cndmask_b32_e32 v56, v239, v56, vcc
	v_cmp_le_i32_e32 vcc, v121, v139
	v_add_u32_e32 v121, 0x72, v120
	s_nop 0
	v_cndmask_b32_e32 v57, v239, v57, vcc
	v_cmp_le_i32_e32 vcc, v121, v139
	v_add_u32_e32 v121, 0x73, v120
	s_nop 0
	v_cndmask_b32_e32 v58, v239, v58, vcc
	v_cmp_le_i32_e32 vcc, v121, v139
	v_add_u32_e32 v121, 0x78, v120
	s_nop 0
	v_cndmask_b32_e32 v59, v239, v59, vcc
	v_cmp_le_i32_e32 vcc, v121, v139
	v_add_u32_e32 v121, 0x79, v120
	s_nop 0
	v_cndmask_b32_e32 v60, v239, v60, vcc
	v_cmp_le_i32_e32 vcc, v121, v139
	v_add_u32_e32 v121, 0x7a, v120
	v_add_u32_e32 v120, 0x7b, v120
	v_cndmask_b32_e32 v61, v239, v61, vcc
	v_cmp_le_i32_e32 vcc, v121, v139
	s_nop 1
	v_cndmask_b32_e32 v62, v239, v62, vcc
	v_cmp_le_i32_e32 vcc, v120, v139
	s_nop 1
	v_cndmask_b32_e32 v63, v239, v63, vcc

; __device__ __forceinline__ unsigned cvt_pk_bf16(float lo, float hi) { const f32x2c_ v = {lo, hi}; const bf16x2c_ b = __builtin_convertvector(v, bf16x2c_); return __builtin_bit_cast(unsigned, b); }
; #define LAS __attribute__((address_space(3)))
; #define MFMA32(a, b, c) __builtin_amdgcn_mfma_f32_32x32x16_bf16(a, b, c, 0, 0, 0)
; __device__ __forceinline__ void attn_unit(int bh, int qb, const bf16_t* QKV, const bf16_t* KF, const float* cstab, const float* qg, bf16_t* MIX, LAS unsigned char* lds) {
;     ...
;             float ps = 0.f;
; #pragma unroll
;             for (int r = 0; r < 16; ++r) { p[r] = __builtin_amdgcn_exp2f(p[r]); ps += p[r]; }
;             lrun += ps;
;             u32x4 w0, w1;
; #pragma unroll
;             for (int k = 0; k < 4; ++k) { w0[k] = cvt_pk_bf16(p[2 * k], p[2 * k + 1]); w1[k] = cvt_pk_bf16(p[8 + 2 * k], p[8 + 2 * k + 1]); }
;             const bf16x8 pb0 = __builtin_bit_cast(bf16x8, w0), pb1 = __builtin_bit_cast(bf16x8, w1);
;             const LAS unsigned char* vp = buf + vtb + (32 * kb) * VROW;
; #pragma unroll
;             for (int db = 0; db < 2; ++db) {
;                 const v4i16_t a0 = __builtin_amdgcn_ds_read_tr16_b64_v4i16((LAS v4i16_t*)(vp + db * 64));
;                 const v4i16_t a1 = __builtin_amdgcn_ds_read_tr16_b64_v4i16((LAS v4i16_t*)(vp + db * 64 + 8 * VROW));
;                 const v4i16_t c0 = __builtin_amdgcn_ds_read_tr16_b64_v4i16((LAS v4i16_t*)(vp + db * 64 + 16 * VROW));
;                 const v4i16_t c1 = __builtin_amdgcn_ds_read_tr16_b64_v4i16((LAS v4i16_t*)(vp + db * 64 + 24 * VROW));
;                 const bf16x8 va = {a0[0], a0[1], a0[2], a0[3], a1[0], a1[1], a1[2], a1[3]}, vc = {c0[0], c0[1], c0[2], c0[3], c1[0], c1[1], c1[2], c1[3]};
;                 __builtin_amdgcn_s_setprio(1);
;                 if (db == 0) { o0 = MFMA32(va, pb0, o0); o0 = MFMA32(vc, pb1, o0); }
;                 else { o1 = MFMA32(va, pb0, o1); o1 = MFMA32(vc, pb1, o1); }
;                 __builtin_amdgcn_s_setprio(0);
;             }
.LBB0_1073:
	v_exp_f32_e32 v48, v48
	v_exp_f32_e32 v49, v49
	v_exp_f32_e32 v50, v50
	v_exp_f32_e32 v51, v51
	v_exp_f32_e32 v121, v52
	v_add_f32_e32 v120, v49, v48
	v_add_f32_e32 v120, v50, v120
	v_add_f32_e32 v120, v51, v120
	v_add_f32_e32 v52, v121, v120
	v_exp_f32_e32 v120, v53
	v_exp_f32_e32 v122, v54
	v_exp_f32_e32 v55, v55
	v_exp_f32_e32 v53, v56
	v_add_f32_e32 v52, v120, v52
	v_exp_f32_e32 v54, v57
	v_add_f32_e32 v52, v122, v52
	v_exp_f32_e32 v56, v58
	v_add_f32_e32 v52, v55, v52
	v_exp_f32_e32 v57, v59
	v_add_f32_e32 v52, v53, v52
	v_exp_f32_e32 v58, v60
	v_add_f32_e32 v52, v54, v52
	v_exp_f32_e32 v59, v61
	v_add_f32_e32 v52, v56, v52
	v_exp_f32_e32 v60, v62
	v_add_f32_e32 v52, v57, v52
	v_exp_f32_e32 v61, v63
	v_add_f32_e32 v52, v58, v52
	v_add_f32_e32 v52, v59, v52
	v_add_f32_e32 v52, v60, v52
	v_add_f32_e32 v123, v61, v52
	v_cvt_pk_bf16_f32 v48, v48, v49
	v_cvt_pk_bf16_f32 v52, v53, v54
	v_cvt_pk_bf16_f32 v49, v50, v51
	v_cvt_pk_bf16_f32 v53, v56, v57
	v_cvt_pk_bf16_f32 v54, v58, v59
	v_cvt_pk_bf16_f32 v51, v122, v55
	v_cvt_pk_bf16_f32 v55, v60, v61
	v_cvt_pk_bf16_f32 v50, v121, v120
	s_setprio 1
	s_waitcnt lgkmcnt(6)
	v_mfma_f32_32x32x16_bf16 v[0:15], v[156:159], v[48:51], v[0:15]
	s_waitcnt lgkmcnt(4)
	v_mfma_f32_32x32x16_bf16 v[0:15], v[160:163], v[52:55], v[0:15]
	s_setprio 0
	s_setprio 1
	s_waitcnt lgkmcnt(2)
	v_mfma_f32_32x32x16_bf16 v[16:31], v[164:167], v[48:51], v[16:31]
	s_waitcnt lgkmcnt(0)
	v_mfma_f32_32x32x16_bf16 v[16:31], v[168:171], v[52:55], v[16:31]
	s_setprio 0
	v_add_f32_e32 v107, v107, v123
	s_branch .LBB0_1077

; #define LAS __attribute__((address_space(3)))
; #define MFMA32(a, b, c) __builtin_amdgcn_mfma_f32_32x32x16_bf16(a, b, c, 0, 0, 0)
; #define ATT_WRITE(bufp) do { *(LAS u32x4*)((bufp) + kofs0) = kr0; if (tid < 256) *(LAS u32x4*)((bufp) + kofs1) = kr1; *(LAS u32x4*)((bufp) + vofs) = vr; } while (0)
; __device__ __forceinline__ void attn_unit(int bh, int qb, const bf16_t* QKV, const bf16_t* KF, const float* cstab, const float* qg, bf16_t* MIX, LAS unsigned char* lds) {
;     ...
;             for (int d0 = 0; d0 < 6; ++d0) p = MFMA32(kfr[d0], qf[d0], p);
;             __builtin_amdgcn_s_setprio(0);
;             if (key0 + 31 > qw) {
; #pragma unroll
;                 for (int r = 0; r < 16; ++r) { const int key = key0 + (r & 3) + 8 * (r >> 2) + 4 * hi; if (key > q) p[r] = -1e30f; }
;     ...
;         if (t + 1 < NT) { LAS unsigned char* nb = lds + ((t + 1) & 1) * BUFB; ATT_WRITE(nb); }
.LBB0_1110:
	s_setprio 1
	s_waitcnt lgkmcnt(5)
	v_mfma_f32_32x32x16_bf16 v[48:63], v[202:205], v[74:77], v[32:47]
	s_waitcnt lgkmcnt(4)
	v_mfma_f32_32x32x16_bf16 v[48:63], v[206:209], v[78:81], v[48:63]
	s_waitcnt lgkmcnt(3)
	v_mfma_f32_32x32x16_bf16 v[48:63], v[210:213], v[82:85], v[48:63]
	s_waitcnt lgkmcnt(2)
	v_mfma_f32_32x32x16_bf16 v[48:63], v[214:217], v[90:93], v[48:63]
	s_waitcnt lgkmcnt(1)
	v_mfma_f32_32x32x16_bf16 v[48:63], v[218:221], v[94:97], v[48:63]
	s_waitcnt lgkmcnt(0)
	v_mfma_f32_32x32x16_bf16 v[48:63], v[222:225], v[98:101], v[48:63]
	s_andn2_b64 vcc, exec, s[4:5]
	s_cbranch_vccnz .Lwskip_b
	s_cmp_eq_u32 s15, 1
	s_cselect_b32 s100, 0x6400, 0
	s_add_i32 s15, s100, 0
	v_add_u32_e32 v173, s15, v103
	s_waitcnt vmcnt(1)
	ds_write_b128 v173, v[70:73]
	s_and_saveexec_b64 s[100:101], s[6:7]
	v_add_u32_e32 v173, s15, v135
	ds_write_b128 v173, v[66:69]
	s_or_b64 exec, exec, s[100:101]
	v_add_u32_e32 v173, s15, v104
	s_waitcnt vmcnt(0)
	ds_write_b128 v173, v[86:89] offset:13312
.Lwskip_b:
	v_add_u32_e32 v172, v119, v115
	ds_read_b64_tr_b16 v[156:157], v172 offset:19456
	ds_read_b64_tr_b16 v[158:159], v172 offset:20992
	ds_read_b64_tr_b16 v[160:161], v172 offset:22528
	ds_read_b64_tr_b16 v[162:163], v172 offset:24064
	ds_read_b64_tr_b16 v[164:165], v172 offset:19520
	ds_read_b64_tr_b16 v[166:167], v172 offset:21056
	ds_read_b64_tr_b16 v[168:169], v172 offset:22592
	ds_read_b64_tr_b16 v[170:171], v172 offset:24128
	s_setprio 0
	s_add_i32 s30, s29, 0x7f
	s_cmp_le_i32 s30, s22
	s_cbranch_scc1 .LBB0_1112
	v_add_u32_e32 v120, s29, v105
	v_add_u32_e32 v121, 0x60, v120
	v_cmp_lt_i32_e32 vcc, v121, v139
	s_nop 4
	v_cndmask_b32_e32 v49, v239, v49, vcc
	v_cmp_le_i32_e32 vcc, v121, v139
	v_add_u32_e32 v121, 0x62, v120
	s_nop 0
	v_cndmask_b32_e32 v48, v239, v48, vcc
	v_cmp_le_i32_e32 vcc, v121, v139
	v_add_u32_e32 v121, 0x63, v120
	s_nop 0
	v_cndmask_b32_e32 v50, v239, v50, vcc
	v_cmp_le_i32_e32 vcc, v121, v139
	v_add_u32_e32 v121, 0x68, v120
	s_nop 0
	v_cndmask_b32_e32 v51, v239, v51, vcc
	v_cmp_le_i32_e32 vcc, v121, v139
	v_add_u32_e32 v121, 0x69, v120
	s_nop 0
	v_cndmask_b32_e32 v52, v239, v52, vcc
	v_cmp_le_i32_e32 vcc, v121, v139
	v_add_u32_e32 v121, 0x6a, v120
	s_nop 0
	v_cndmask_b32_e32 v53, v239, v53, vcc
	v_cmp_le_i32_e32 vcc, v121, v139
	v_add_u32_e32 v121, 0x6b, v120
	s_nop 0
	v_cndmask_b32_e32 v54, v239, v54, vcc
	v_cmp_le_i32_e32 vcc, v121, v139
	v_add_u32_e32 v121, 0x70, v120
	s_nop 0
	v_cndmask_b32_e32 v55, v239, v55, vcc
	v_cmp_le_i32_e32 vcc, v121, v139
	v_add_u32_e32 v121, 0x71, v120
	s_nop 0
	v_cndmask_b32_e32 v56, v239, v56, vcc
	v_cmp_le_i32_e32 vcc, v121, v139
	v_add_u32_e32 v121, 0x72, v120
	s_nop 0
	v_cndmask_b32_e32 v57, v239, v57, vcc
	v_cmp_le_i32_e32 vcc, v121, v139
	v_add_u32_e32 v121, 0x73, v120
	s_nop 0
	v_cndmask_b32_e32 v58, v239, v58, vcc
	v_cmp_le_i32_e32 vcc, v121, v139
	v_add_u32_e32 v121, 0x78, v120
	s_nop 0
	v_cndmask_b32_e32 v59, v239, v59, vcc
	v_cmp_le_i32_e32 vcc, v121, v139
	v_add_u32_e32 v121, 0x79, v120
	s_nop 0
	v_cndmask_b32_e32 v60, v239, v60, vcc
	v_cmp_le_i32_e32 vcc, v121, v139
	v_add_u32_e32 v121, 0x7a, v120
	v_add_u32_e32 v120, 0x7b, v120
	v_cndmask_b32_e32 v61, v239, v61, vcc
	v_cmp_le_i32_e32 vcc, v121, v139
	s_nop 1
	v_cndmask_b32_e32 v62, v239, v62, vcc
	v_cmp_le_i32_e32 vcc, v120, v139
	s_nop 1
	v_cndmask_b32_e32 v63, v239, v63, vcc
